# attention bias-table fill: 8 rpb loads in flight per table instead of serialized load-wait-write
# speedup vs baseline: 1.0056x; 1.0054x over previous
.LBB0_197:
	global_load_dword v176, v[0:1], off
	global_load_dword v177, v[0:1], off offset:256
	global_load_dword v178, v[0:1], off offset:512
	global_load_dword v179, v[0:1], off offset:768
	global_load_dword v180, v[0:1], off offset:1024
	global_load_dword v181, v[0:1], off offset:1280
	global_load_dword v182, v[0:1], off offset:1536
	v_cmp_gt_u32_e32 vcc, 17, v4
	s_and_saveexec_b64 s[6:7], vcc
	global_load_dword v183, v[0:1], off offset:1792
	s_mov_b64 exec, s[6:7]
	v_add_u32_e32 v192, 0, v4
	v_mul_u32_u24_e32 v193, 0x843, v192
	v_lshrrev_b32_e32 v193, 16, v193
	v_sub_u32_e32 v190, v192, v193
	v_lshrrev_b32_e32 v190, 1, v190
	v_add_u32_e32 v190, v190, v193
	v_lshrrev_b32_e32 v190, 4, v190
	v_mul_u32_u24_e32 v193, 31, v190
	v_sub_u32_e32 v193, v192, v193
	v_lshlrev_b32_e32 v190, 7, v190
	v_lshlrev_b32_e32 v193, 2, v193
	v_add3_u32 v184, s2, v190, v193
	v_add_u32_e32 v192, 64, v4
	v_mul_u32_u24_e32 v193, 0x843, v192
	v_lshrrev_b32_e32 v193, 16, v193
	v_sub_u32_e32 v190, v192, v193
	v_lshrrev_b32_e32 v190, 1, v190
	v_add_u32_e32 v190, v190, v193
	v_lshrrev_b32_e32 v190, 4, v190
	v_mul_u32_u24_e32 v193, 31, v190
	v_sub_u32_e32 v193, v192, v193
	v_lshlrev_b32_e32 v190, 7, v190
	v_lshlrev_b32_e32 v193, 2, v193
	v_add3_u32 v185, s2, v190, v193
	v_add_u32_e32 v192, 128, v4
	v_mul_u32_u24_e32 v193, 0x843, v192
	v_lshrrev_b32_e32 v193, 16, v193
	v_sub_u32_e32 v190, v192, v193
	v_lshrrev_b32_e32 v190, 1, v190
	v_add_u32_e32 v190, v190, v193
	v_lshrrev_b32_e32 v190, 4, v190
	v_mul_u32_u24_e32 v193, 31, v190
	v_sub_u32_e32 v193, v192, v193
	v_lshlrev_b32_e32 v190, 7, v190
	v_lshlrev_b32_e32 v193, 2, v193
	v_add3_u32 v186, s2, v190, v193
	v_add_u32_e32 v192, 192, v4
	v_mul_u32_u24_e32 v193, 0x843, v192
	v_lshrrev_b32_e32 v193, 16, v193
	v_sub_u32_e32 v190, v192, v193
	v_lshrrev_b32_e32 v190, 1, v190
	v_add_u32_e32 v190, v190, v193
	v_lshrrev_b32_e32 v190, 4, v190
	v_mul_u32_u24_e32 v193, 31, v190
	v_sub_u32_e32 v193, v192, v193
	v_lshlrev_b32_e32 v190, 7, v190
	v_lshlrev_b32_e32 v193, 2, v193
	v_add3_u32 v187, s2, v190, v193
	v_add_u32_e32 v192, 256, v4
	v_mul_u32_u24_e32 v193, 0x843, v192
	v_lshrrev_b32_e32 v193, 16, v193
	v_sub_u32_e32 v190, v192, v193
	v_lshrrev_b32_e32 v190, 1, v190
	v_add_u32_e32 v190, v190, v193
	v_lshrrev_b32_e32 v190, 4, v190
	v_mul_u32_u24_e32 v193, 31, v190
	v_sub_u32_e32 v193, v192, v193
	v_lshlrev_b32_e32 v190, 7, v190
	v_lshlrev_b32_e32 v193, 2, v193
	v_add3_u32 v188, s2, v190, v193
	v_add_u32_e32 v192, 320, v4
	v_mul_u32_u24_e32 v193, 0x843, v192
	v_lshrrev_b32_e32 v193, 16, v193
	v_sub_u32_e32 v190, v192, v193
	v_lshrrev_b32_e32 v190, 1, v190
	v_add_u32_e32 v190, v190, v193
	v_lshrrev_b32_e32 v190, 4, v190
	v_mul_u32_u24_e32 v193, 31, v190
	v_sub_u32_e32 v193, v192, v193
	v_lshlrev_b32_e32 v190, 7, v190
	v_lshlrev_b32_e32 v193, 2, v193
	v_add3_u32 v189, s2, v190, v193
	v_add_u32_e32 v192, 384, v4
	v_mul_u32_u24_e32 v193, 0x843, v192
	v_lshrrev_b32_e32 v193, 16, v193
	v_sub_u32_e32 v190, v192, v193
	v_lshrrev_b32_e32 v190, 1, v190
	v_add_u32_e32 v190, v190, v193
	v_lshrrev_b32_e32 v190, 4, v190
	v_mul_u32_u24_e32 v193, 31, v190
	v_sub_u32_e32 v193, v192, v193
	v_lshlrev_b32_e32 v190, 7, v190
	v_lshlrev_b32_e32 v193, 2, v193
	v_add3_u32 v204, s2, v190, v193
	v_add_u32_e32 v192, 448, v4
	v_mul_u32_u24_e32 v193, 0x843, v192
	v_lshrrev_b32_e32 v193, 16, v193
	v_sub_u32_e32 v190, v192, v193
	v_lshrrev_b32_e32 v190, 1, v190
	v_add_u32_e32 v190, v190, v193
	v_lshrrev_b32_e32 v190, 4, v190
	v_mul_u32_u24_e32 v193, 31, v190
	v_sub_u32_e32 v193, v192, v193
	v_lshlrev_b32_e32 v190, 7, v190
	v_lshlrev_b32_e32 v193, 2, v193
	v_add3_u32 v205, s2, v190, v193
	s_waitcnt vmcnt(0)
	v_mul_f32_e32 v176, 0x3fb8aa3b, v176
	ds_write_b32 v184, v176 offset:1024
	v_mul_f32_e32 v177, 0x3fb8aa3b, v177
	ds_write_b32 v185, v177 offset:1024
	v_mul_f32_e32 v178, 0x3fb8aa3b, v178
	ds_write_b32 v186, v178 offset:1024
	v_mul_f32_e32 v179, 0x3fb8aa3b, v179
	ds_write_b32 v187, v179 offset:1024
	v_mul_f32_e32 v180, 0x3fb8aa3b, v180
	ds_write_b32 v188, v180 offset:1024
	v_mul_f32_e32 v181, 0x3fb8aa3b, v181
	ds_write_b32 v189, v181 offset:1024
	v_mul_f32_e32 v182, 0x3fb8aa3b, v182
	ds_write_b32 v204, v182 offset:1024
	s_and_saveexec_b64 s[6:7], vcc
	v_mul_f32_e32 v183, 0x3fb8aa3b, v183
	ds_write_b32 v205, v183 offset:1024
	s_mov_b64 exec, s[6:7]
	s_or_b64 exec, exec, s[0:1]
	s_or_b32 s0, s3, 4
	v_readlane_b32 s36, v253, 48
	s_mul_hi_i32 s1, s0, 0x744
	s_mulk_i32 s0, 0x744
	v_readlane_b32 s40, v253, 52
	v_readlane_b32 s41, v253, 53
	s_add_u32 s0, s40, s0
	s_addc_u32 s1, s41, s1
	v_lshl_add_u64 v[0:1], s[0:1], 0, v[8:9]
	s_mov_b64 s[0:1], 0
	ds_write2st64_b32 v3, v9, v9 offset0:12 offset1:13
	ds_write2st64_b32 v3, v9, v9 offset0:14 offset1:15
	ds_write2st64_b32 v3, v9, v9 offset0:16 offset1:17
	ds_write2st64_b32 v3, v9, v9 offset0:18 offset1:19
	v_readlane_b32 s37, v253, 49
	v_readlane_b32 s38, v253, 50
	v_readlane_b32 s39, v253, 51
	v_readlane_b32 s42, v253, 54
	v_readlane_b32 s43, v253, 55
	v_readlane_b32 s44, v253, 56
	v_readlane_b32 s45, v253, 57
	v_readlane_b32 s46, v253, 58
	v_readlane_b32 s47, v253, 59
	v_readlane_b32 s48, v253, 60
	v_readlane_b32 s49, v253, 61
	v_readlane_b32 s50, v253, 62
	v_readlane_b32 s51, v253, 63
.LBB0_199:
	global_load_dword v176, v[0:1], off
	global_load_dword v177, v[0:1], off offset:256
	global_load_dword v178, v[0:1], off offset:512
	global_load_dword v179, v[0:1], off offset:768
	global_load_dword v180, v[0:1], off offset:1024
	global_load_dword v181, v[0:1], off offset:1280
	global_load_dword v182, v[0:1], off offset:1536
	v_cmp_gt_u32_e32 vcc, 17, v2
	s_and_saveexec_b64 s[6:7], vcc
	global_load_dword v183, v[0:1], off offset:1792
	s_mov_b64 exec, s[6:7]
	v_add_u32_e32 v192, 0, v2
	v_mul_u32_u24_e32 v193, 0x843, v192
	v_lshrrev_b32_e32 v193, 16, v193
	v_sub_u32_e32 v190, v192, v193
	v_lshrrev_b32_e32 v190, 1, v190
	v_add_u32_e32 v190, v190, v193
	v_lshrrev_b32_e32 v190, 4, v190
	v_mul_u32_u24_e32 v193, 31, v190
	v_sub_u32_e32 v193, v192, v193
	v_lshlrev_b32_e32 v190, 7, v190
	v_lshlrev_b32_e32 v193, 2, v193
	v_add3_u32 v184, s2, v190, v193
	v_add_u32_e32 v192, 64, v2
	v_mul_u32_u24_e32 v193, 0x843, v192
	v_lshrrev_b32_e32 v193, 16, v193
	v_sub_u32_e32 v190, v192, v193
	v_lshrrev_b32_e32 v190, 1, v190
	v_add_u32_e32 v190, v190, v193
	v_lshrrev_b32_e32 v190, 4, v190
	v_mul_u32_u24_e32 v193, 31, v190
	v_sub_u32_e32 v193, v192, v193
	v_lshlrev_b32_e32 v190, 7, v190
	v_lshlrev_b32_e32 v193, 2, v193
	v_add3_u32 v185, s2, v190, v193
	v_add_u32_e32 v192, 128, v2
	v_mul_u32_u24_e32 v193, 0x843, v192
	v_lshrrev_b32_e32 v193, 16, v193
	v_sub_u32_e32 v190, v192, v193
	v_lshrrev_b32_e32 v190, 1, v190
	v_add_u32_e32 v190, v190, v193
	v_lshrrev_b32_e32 v190, 4, v190
	v_mul_u32_u24_e32 v193, 31, v190
	v_sub_u32_e32 v193, v192, v193
	v_lshlrev_b32_e32 v190, 7, v190
	v_lshlrev_b32_e32 v193, 2, v193
	v_add3_u32 v186, s2, v190, v193
	v_add_u32_e32 v192, 192, v2
	v_mul_u32_u24_e32 v193, 0x843, v192
	v_lshrrev_b32_e32 v193, 16, v193
	v_sub_u32_e32 v190, v192, v193
	v_lshrrev_b32_e32 v190, 1, v190
	v_add_u32_e32 v190, v190, v193
	v_lshrrev_b32_e32 v190, 4, v190
	v_mul_u32_u24_e32 v193, 31, v190
	v_sub_u32_e32 v193, v192, v193
	v_lshlrev_b32_e32 v190, 7, v190
	v_lshlrev_b32_e32 v193, 2, v193
	v_add3_u32 v187, s2, v190, v193
	v_add_u32_e32 v192, 256, v2
	v_mul_u32_u24_e32 v193, 0x843, v192
	v_lshrrev_b32_e32 v193, 16, v193
	v_sub_u32_e32 v190, v192, v193
	v_lshrrev_b32_e32 v190, 1, v190
	v_add_u32_e32 v190, v190, v193
	v_lshrrev_b32_e32 v190, 4, v190
	v_mul_u32_u24_e32 v193, 31, v190
	v_sub_u32_e32 v193, v192, v193
	v_lshlrev_b32_e32 v190, 7, v190
	v_lshlrev_b32_e32 v193, 2, v193
	v_add3_u32 v188, s2, v190, v193
	v_add_u32_e32 v192, 320, v2
	v_mul_u32_u24_e32 v193, 0x843, v192
	v_lshrrev_b32_e32 v193, 16, v193
	v_sub_u32_e32 v190, v192, v193
	v_lshrrev_b32_e32 v190, 1, v190
	v_add_u32_e32 v190, v190, v193
	v_lshrrev_b32_e32 v190, 4, v190
	v_mul_u32_u24_e32 v193, 31, v190
	v_sub_u32_e32 v193, v192, v193
	v_lshlrev_b32_e32 v190, 7, v190
	v_lshlrev_b32_e32 v193, 2, v193
	v_add3_u32 v189, s2, v190, v193
	v_add_u32_e32 v192, 384, v2
	v_mul_u32_u24_e32 v193, 0x843, v192
	v_lshrrev_b32_e32 v193, 16, v193
	v_sub_u32_e32 v190, v192, v193
	v_lshrrev_b32_e32 v190, 1, v190
	v_add_u32_e32 v190, v190, v193
	v_lshrrev_b32_e32 v190, 4, v190
	v_mul_u32_u24_e32 v193, 31, v190
	v_sub_u32_e32 v193, v192, v193
	v_lshlrev_b32_e32 v190, 7, v190
	v_lshlrev_b32_e32 v193, 2, v193
	v_add3_u32 v204, s2, v190, v193
	v_add_u32_e32 v192, 448, v2
	v_mul_u32_u24_e32 v193, 0x843, v192
	v_lshrrev_b32_e32 v193, 16, v193
	v_sub_u32_e32 v190, v192, v193
	v_lshrrev_b32_e32 v190, 1, v190
	v_add_u32_e32 v190, v190, v193
	v_lshrrev_b32_e32 v190, 4, v190
	v_mul_u32_u24_e32 v193, 31, v190
	v_sub_u32_e32 v193, v192, v193
	v_lshlrev_b32_e32 v190, 7, v190
	v_lshlrev_b32_e32 v193, 2, v193
	v_add3_u32 v205, s2, v190, v193
	s_waitcnt vmcnt(0)
	v_mul_f32_e32 v176, 0x3fb8aa3b, v176
	ds_write_b32 v184, v176 offset:3072
	v_mul_f32_e32 v177, 0x3fb8aa3b, v177
	ds_write_b32 v185, v177 offset:3072
	v_mul_f32_e32 v178, 0x3fb8aa3b, v178
	ds_write_b32 v186, v178 offset:3072
	v_mul_f32_e32 v179, 0x3fb8aa3b, v179
	ds_write_b32 v187, v179 offset:3072
	v_mul_f32_e32 v180, 0x3fb8aa3b, v180
	ds_write_b32 v188, v180 offset:3072
	v_mul_f32_e32 v181, 0x3fb8aa3b, v181
	ds_write_b32 v189, v181 offset:3072
	v_mul_f32_e32 v182, 0x3fb8aa3b, v182
	ds_write_b32 v204, v182 offset:3072
	s_and_saveexec_b64 s[6:7], vcc
	v_mul_f32_e32 v183, 0x3fb8aa3b, v183
	ds_write_b32 v205, v183 offset:3072
	s_mov_b64 exec, s[6:7]
	s_or_b64 exec, exec, s[0:1]
	s_branch .LBB0_204
